# BR GEMM epilogue (EpiGate2) rewritten: gate/merge loads of a half tile issued up front, counted vmcnt(7) waits instead of 16-32 serialized vmcnt(0) round trips; plus EW LDS gain staging
# speedup vs baseline: 1.0052x; 1.0052x over previous
; __device__ __forceinline__ unsigned cvt_pk_bf16(float lo, float hi) { const f32x2_cv v = {lo, hi}; const bf16x2_cv b = __builtin_convertvector(v, bf16x2_cv); return __builtin_bit_cast(unsigned, b); }
; __device__ __forceinline__ float bf_lo(unsigned w) { return __uint_as_float(w << 16); }
; __device__ __forceinline__ float bf_hi(unsigned w) { return __uint_as_float(w & 0xffff0000u); }
;     __device__ __forceinline__ void operator()(const f32x4 (&acc)[2][2][4][2], const Unit& u, int wr, int wc, int fr, int fq) const {
;         const bool add = u.pm >= 64;
;         const int row0 = (u.pm & 63) * BM + wr * 64 + fr, col0 = (u.pn & 7) * BM + wc * 32 + 8 * fq, gcol0 = add ? 2048 : 0;
; #pragma unroll
;         for (int ai = 0; ai < 2; ++ai)
; #pragma unroll
;             for (int m = 0; m < 4; ++m) { const int row = row0 + ai * HALF + m * 16;
; #pragma unroll
;                 for (int bj = 0; bj < 2; ++bj) { const int col = col0 + bj * HALF;
;                     const u32x4 g = *(const u32x4*)(G + (size_t)row * GW + gcol0 + col);
;                     float r[8];
;                     r[0] = acc[ai][bj][m][0][0] * bf_lo(g.x); r[1] = acc[ai][bj][m][0][1] * bf_hi(g.x); r[2] = acc[ai][bj][m][0][2] * bf_lo(g.y); r[3] = acc[ai][bj][m][0][3] * bf_hi(g.y);
;                     r[4] = acc[ai][bj][m][1][0] * bf_lo(g.z); r[5] = acc[ai][bj][m][1][1] * bf_hi(g.z); r[6] = acc[ai][bj][m][1][2] * bf_lo(g.w); r[7] = acc[ai][bj][m][1][3] * bf_hi(g.w);
;                     bf16_t* dst = O + (size_t)row * DM + col;
;                     if (add) { const u32x4 o = *(const u32x4*)dst;
;                         r[0] += bf_lo(o.x); r[1] += bf_hi(o.x); r[2] += bf_lo(o.y); r[3] += bf_hi(o.y); r[4] += bf_lo(o.z); r[5] += bf_hi(o.z); r[6] += bf_lo(o.w); r[7] += bf_hi(o.w); }
;                     u32x4 w; w.x = cvt_pk_bf16(r[0], r[1]); w.y = cvt_pk_bf16(r[2], r[3]); w.z = cvt_pk_bf16(r[4], r[5]); w.w = cvt_pk_bf16(r[6], r[7]);
;                     *(u32x4*)dst = w; } }
.LBB0_89:
	s_lshl_b32 s4, s6, 8
	s_and_b32 s7, s4, 0x3f00
	s_lshl_b32 s4, s80, 8
	s_and_b32 s15, s4, 0x700
	s_cmp_gt_i32 s6, 63
	s_cselect_b64 s[4:5], -1, 0
	v_add_u32_e32 v140, s7, v146
	s_and_b64 s[28:29], s[4:5], exec
	v_ashrrev_i32_e32 v141, 31, v140
	s_cselect_b32 s24, 0x800, 0
	v_lshlrev_b64 v[142:143], 13, v[140:141]
	s_lshl_b32 s24, s24, 1
	v_or_b32_e32 v150, s15, v148
	v_lshl_add_u64 v[142:143], s[72:73], 0, v[142:143]
	v_lshl_add_u64 v[142:143], v[142:143], 0, s[24:25]
	v_lshlrev_b32_e32 v160, 1, v150
	v_lshl_add_u64 v[142:143], v[142:143], 0, v[160:161]
	v_lshlrev_b64 v[144:145], 12, v[140:141]
	v_lshl_add_u64 v[144:145], s[8:9], 0, v[144:145]
	v_lshl_add_u64 v[144:145], v[144:145], 0, v[160:161]
	s_mov_b64 s[98:99], 0x20000
	s_mov_b64 s[94:95], 0x10000
	s_and_b64 vcc, exec, s[4:5]
	v_lshl_add_u64 v[152:153], v[144:145], 0, s[94:95]
	v_lshl_add_u64 v[154:155], v[152:153], 0, s[94:95]
	v_lshl_add_u64 v[156:157], v[154:155], 0, s[94:95]
	global_load_dwordx4 v[164:167], v[142:143], off
	global_load_dwordx4 v[168:171], v[142:143], off offset:256
	v_lshl_add_u64 v[142:143], v[142:143], 0, s[98:99]
	global_load_dwordx4 v[172:175], v[142:143], off
	global_load_dwordx4 v[176:179], v[142:143], off offset:256
	v_lshl_add_u64 v[142:143], v[142:143], 0, s[98:99]
	global_load_dwordx4 v[180:183], v[142:143], off
	global_load_dwordx4 v[184:187], v[142:143], off offset:256
	v_lshl_add_u64 v[142:143], v[142:143], 0, s[98:99]
	global_load_dwordx4 v[188:191], v[142:143], off
	global_load_dwordx4 v[192:195], v[142:143], off offset:256
	s_mov_b64 s[28:29], 0xa0000
	v_lshl_add_u64 v[142:143], v[142:143], 0, s[28:29]
	s_cbranch_vccz .Lbr_nl_0
	global_load_dwordx4 v[196:199], v[144:145], off
	global_load_dwordx4 v[222:225], v[144:145], off offset:256
	global_load_dwordx4 v[226:229], v[152:153], off
	global_load_dwordx4 v[230:233], v[152:153], off offset:256
	global_load_dwordx4 v[234:237], v[154:155], off
	global_load_dwordx4 v[238:241], v[154:155], off offset:256
	global_load_dwordx4 v[242:245], v[156:157], off
	global_load_dwordx4 v[246:249], v[156:157], off offset:256
.Lbr_nl_0:
	s_waitcnt vmcnt(7)
	v_lshlrev_b32_e32 v250, 16, v164
	v_and_b32_e32 v251, 0xffff0000, v164
	v_lshlrev_b32_e32 v252, 16, v165
	v_and_b32_e32 v253, 0xffff0000, v165
	v_lshlrev_b32_e32 v158, 16, v166
	v_and_b32_e32 v159, 0xffff0000, v166
	v_lshlrev_b32_e32 v140, 16, v167
	v_and_b32_e32 v141, 0xffff0000, v167
	v_pk_mul_f32 v[124:125], v[124:125], v[250:251]
	v_pk_mul_f32 v[126:127], v[126:127], v[252:253]
	v_pk_mul_f32 v[120:121], v[120:121], v[158:159]
	v_pk_mul_f32 v[122:123], v[122:123], v[140:141]
	s_cbranch_vccz .Lbr_na_0_0
	v_lshlrev_b32_e32 v250, 16, v196
	v_and_b32_e32 v251, 0xffff0000, v196
	v_lshlrev_b32_e32 v252, 16, v197
	v_and_b32_e32 v253, 0xffff0000, v197
	v_lshlrev_b32_e32 v158, 16, v198
	v_and_b32_e32 v159, 0xffff0000, v198
	v_lshlrev_b32_e32 v140, 16, v199
	v_and_b32_e32 v141, 0xffff0000, v199
	v_pk_add_f32 v[124:125], v[124:125], v[250:251]
	v_pk_add_f32 v[126:127], v[126:127], v[252:253]
	v_pk_add_f32 v[120:121], v[120:121], v[158:159]
	v_pk_add_f32 v[122:123], v[122:123], v[140:141]
.Lbr_na_0_0:
	v_cvt_pk_bf16_f32 v124, v124, v125
	v_cvt_pk_bf16_f32 v125, v126, v127
	v_cvt_pk_bf16_f32 v126, v120, v121
	v_cvt_pk_bf16_f32 v127, v122, v123
	global_store_dwordx4 v[144:145], v[124:127], off
	s_waitcnt vmcnt(7)
	v_lshlrev_b32_e32 v250, 16, v168
	v_and_b32_e32 v251, 0xffff0000, v168
	v_lshlrev_b32_e32 v252, 16, v169
	v_and_b32_e32 v253, 0xffff0000, v169
	v_lshlrev_b32_e32 v158, 16, v170
	v_and_b32_e32 v159, 0xffff0000, v170
	v_lshlrev_b32_e32 v140, 16, v171
	v_and_b32_e32 v141, 0xffff0000, v171
	v_pk_mul_f32 v[116:117], v[116:117], v[250:251]
	v_pk_mul_f32 v[118:119], v[118:119], v[252:253]
	v_pk_mul_f32 v[112:113], v[112:113], v[158:159]
	v_pk_mul_f32 v[114:115], v[114:115], v[140:141]
	s_cbranch_vccz .Lbr_na_0_1
	v_lshlrev_b32_e32 v250, 16, v222
	v_and_b32_e32 v251, 0xffff0000, v222
	v_lshlrev_b32_e32 v252, 16, v223
	v_and_b32_e32 v253, 0xffff0000, v223
	v_lshlrev_b32_e32 v158, 16, v224
	v_and_b32_e32 v159, 0xffff0000, v224
	v_lshlrev_b32_e32 v140, 16, v225
	v_and_b32_e32 v141, 0xffff0000, v225
	v_pk_add_f32 v[116:117], v[116:117], v[250:251]
	v_pk_add_f32 v[118:119], v[118:119], v[252:253]
	v_pk_add_f32 v[112:113], v[112:113], v[158:159]
	v_pk_add_f32 v[114:115], v[114:115], v[140:141]
.Lbr_na_0_1:
	v_cvt_pk_bf16_f32 v116, v116, v117
	v_cvt_pk_bf16_f32 v117, v118, v119
	v_cvt_pk_bf16_f32 v118, v112, v113
	v_cvt_pk_bf16_f32 v119, v114, v115
	global_store_dwordx4 v[144:145], v[116:119], off offset:256
	s_waitcnt vmcnt(7)
	v_lshlrev_b32_e32 v250, 16, v172
	v_and_b32_e32 v251, 0xffff0000, v172
	v_lshlrev_b32_e32 v252, 16, v173
	v_and_b32_e32 v253, 0xffff0000, v173
	v_lshlrev_b32_e32 v158, 16, v174
	v_and_b32_e32 v159, 0xffff0000, v174
	v_lshlrev_b32_e32 v140, 16, v175
	v_and_b32_e32 v141, 0xffff0000, v175
	v_pk_mul_f32 v[108:109], v[108:109], v[250:251]
	v_pk_mul_f32 v[110:111], v[110:111], v[252:253]
	v_pk_mul_f32 v[104:105], v[104:105], v[158:159]
	v_pk_mul_f32 v[106:107], v[106:107], v[140:141]
	s_cbranch_vccz .Lbr_na_0_2
	v_lshlrev_b32_e32 v250, 16, v226
	v_and_b32_e32 v251, 0xffff0000, v226
	v_lshlrev_b32_e32 v252, 16, v227
	v_and_b32_e32 v253, 0xffff0000, v227
	v_lshlrev_b32_e32 v158, 16, v228
	v_and_b32_e32 v159, 0xffff0000, v228
	v_lshlrev_b32_e32 v140, 16, v229
	v_and_b32_e32 v141, 0xffff0000, v229
	v_pk_add_f32 v[108:109], v[108:109], v[250:251]
	v_pk_add_f32 v[110:111], v[110:111], v[252:253]
	v_pk_add_f32 v[104:105], v[104:105], v[158:159]
	v_pk_add_f32 v[106:107], v[106:107], v[140:141]
; __device__ __forceinline__ unsigned cvt_pk_bf16(float lo, float hi) { const f32x2_cv v = {lo, hi}; const bf16x2_cv b = __builtin_convertvector(v, bf16x2_cv); return __builtin_bit_cast(unsigned, b); }
; __device__ __forceinline__ float bf_lo(unsigned w) { return __uint_as_float(w << 16); }
; __device__ __forceinline__ float bf_hi(unsigned w) { return __uint_as_float(w & 0xffff0000u); }
;     __device__ __forceinline__ void operator()(const f32x4 (&acc)[2][2][4][2], const Unit& u, int wr, int wc, int fr, int fq) const {
;     ...
;             for (int m = 0; m < 4; ++m) { const int row = row0 + ai * HALF + m * 16;
; #pragma unroll
;                 for (int bj = 0; bj < 2; ++bj) { const int col = col0 + bj * HALF;
;                     const u32x4 g = *(const u32x4*)(G + (size_t)row * GW + gcol0 + col);
;                     float r[8];
;                     r[0] = acc[ai][bj][m][0][0] * bf_lo(g.x); r[1] = acc[ai][bj][m][0][1] * bf_hi(g.x); r[2] = acc[ai][bj][m][0][2] * bf_lo(g.y); r[3] = acc[ai][bj][m][0][3] * bf_hi(g.y);
;                     r[4] = acc[ai][bj][m][1][0] * bf_lo(g.z); r[5] = acc[ai][bj][m][1][1] * bf_hi(g.z); r[6] = acc[ai][bj][m][1][2] * bf_lo(g.w); r[7] = acc[ai][bj][m][1][3] * bf_hi(g.w);
;                     bf16_t* dst = O + (size_t)row * DM + col;
;                     if (add) { const u32x4 o = *(const u32x4*)dst;
;                         r[0] += bf_lo(o.x); r[1] += bf_hi(o.x); r[2] += bf_lo(o.y); r[3] += bf_hi(o.y); r[4] += bf_lo(o.z); r[5] += bf_hi(o.z); r[6] += bf_lo(o.w); r[7] += bf_hi(o.w); }
;                     u32x4 w; w.x = cvt_pk_bf16(r[0], r[1]); w.y = cvt_pk_bf16(r[2], r[3]); w.z = cvt_pk_bf16(r[4], r[5]); w.w = cvt_pk_bf16(r[6], r[7]);
;                     *(u32x4*)dst = w; } }
.Lbr_na_0_2:
	v_cvt_pk_bf16_f32 v108, v108, v109
	v_cvt_pk_bf16_f32 v109, v110, v111
	v_cvt_pk_bf16_f32 v110, v104, v105
	v_cvt_pk_bf16_f32 v111, v106, v107
	global_store_dwordx4 v[152:153], v[108:111], off
	s_waitcnt vmcnt(7)
	v_lshlrev_b32_e32 v250, 16, v176
	v_and_b32_e32 v251, 0xffff0000, v176
	v_lshlrev_b32_e32 v252, 16, v177
	v_and_b32_e32 v253, 0xffff0000, v177
	v_lshlrev_b32_e32 v158, 16, v178
	v_and_b32_e32 v159, 0xffff0000, v178
	v_lshlrev_b32_e32 v140, 16, v179
	v_and_b32_e32 v141, 0xffff0000, v179
	v_pk_mul_f32 v[100:101], v[100:101], v[250:251]
	v_pk_mul_f32 v[102:103], v[102:103], v[252:253]
	v_pk_mul_f32 v[96:97], v[96:97], v[158:159]
	v_pk_mul_f32 v[98:99], v[98:99], v[140:141]
	s_cbranch_vccz .Lbr_na_0_3
	v_lshlrev_b32_e32 v250, 16, v230
	v_and_b32_e32 v251, 0xffff0000, v230
	v_lshlrev_b32_e32 v252, 16, v231
	v_and_b32_e32 v253, 0xffff0000, v231
	v_lshlrev_b32_e32 v158, 16, v232
	v_and_b32_e32 v159, 0xffff0000, v232
	v_lshlrev_b32_e32 v140, 16, v233
	v_and_b32_e32 v141, 0xffff0000, v233
	v_pk_add_f32 v[100:101], v[100:101], v[250:251]
	v_pk_add_f32 v[102:103], v[102:103], v[252:253]
	v_pk_add_f32 v[96:97], v[96:97], v[158:159]
	v_pk_add_f32 v[98:99], v[98:99], v[140:141]
.Lbr_na_0_3:
	v_cvt_pk_bf16_f32 v100, v100, v101
	v_cvt_pk_bf16_f32 v101, v102, v103
	v_cvt_pk_bf16_f32 v102, v96, v97
	v_cvt_pk_bf16_f32 v103, v98, v99
	global_store_dwordx4 v[152:153], v[100:103], off offset:256
	s_waitcnt vmcnt(7)
	v_lshlrev_b32_e32 v250, 16, v180
	v_and_b32_e32 v251, 0xffff0000, v180
	v_lshlrev_b32_e32 v252, 16, v181
	v_and_b32_e32 v253, 0xffff0000, v181
	v_lshlrev_b32_e32 v158, 16, v182
	v_and_b32_e32 v159, 0xffff0000, v182
	v_lshlrev_b32_e32 v140, 16, v183
	v_and_b32_e32 v141, 0xffff0000, v183
	v_pk_mul_f32 v[92:93], v[92:93], v[250:251]
	v_pk_mul_f32 v[94:95], v[94:95], v[252:253]
	v_pk_mul_f32 v[88:89], v[88:89], v[158:159]
	v_pk_mul_f32 v[90:91], v[90:91], v[140:141]
	s_cbranch_vccz .Lbr_na_0_4
	v_lshlrev_b32_e32 v250, 16, v234
	v_and_b32_e32 v251, 0xffff0000, v234
	v_lshlrev_b32_e32 v252, 16, v235
	v_and_b32_e32 v253, 0xffff0000, v235
	v_lshlrev_b32_e32 v158, 16, v236
	v_and_b32_e32 v159, 0xffff0000, v236
	v_lshlrev_b32_e32 v140, 16, v237
	v_and_b32_e32 v141, 0xffff0000, v237
	v_pk_add_f32 v[92:93], v[92:93], v[250:251]
	v_pk_add_f32 v[94:95], v[94:95], v[252:253]
	v_pk_add_f32 v[88:89], v[88:89], v[158:159]
	v_pk_add_f32 v[90:91], v[90:91], v[140:141]
.Lbr_na_0_4:
	v_cvt_pk_bf16_f32 v92, v92, v93
	v_cvt_pk_bf16_f32 v93, v94, v95
	v_cvt_pk_bf16_f32 v94, v88, v89
	v_cvt_pk_bf16_f32 v95, v90, v91
	global_store_dwordx4 v[154:155], v[92:95], off
	s_waitcnt vmcnt(7)
	v_lshlrev_b32_e32 v250, 16, v184
	v_and_b32_e32 v251, 0xffff0000, v184
	v_lshlrev_b32_e32 v252, 16, v185
	v_and_b32_e32 v253, 0xffff0000, v185
	v_lshlrev_b32_e32 v158, 16, v186
	v_and_b32_e32 v159, 0xffff0000, v186
	v_lshlrev_b32_e32 v140, 16, v187
	v_and_b32_e32 v141, 0xffff0000, v187
	v_pk_mul_f32 v[84:85], v[84:85], v[250:251]
	v_pk_mul_f32 v[86:87], v[86:87], v[252:253]
	v_pk_mul_f32 v[80:81], v[80:81], v[158:159]
	v_pk_mul_f32 v[82:83], v[82:83], v[140:141]
	s_cbranch_vccz .Lbr_na_0_5
	v_lshlrev_b32_e32 v250, 16, v238
	v_and_b32_e32 v251, 0xffff0000, v238
	v_lshlrev_b32_e32 v252, 16, v239
	v_and_b32_e32 v253, 0xffff0000, v239
	v_lshlrev_b32_e32 v158, 16, v240
	v_and_b32_e32 v159, 0xffff0000, v240
	v_lshlrev_b32_e32 v140, 16, v241
	v_and_b32_e32 v141, 0xffff0000, v241
	v_pk_add_f32 v[84:85], v[84:85], v[250:251]
	v_pk_add_f32 v[86:87], v[86:87], v[252:253]
	v_pk_add_f32 v[80:81], v[80:81], v[158:159]
	v_pk_add_f32 v[82:83], v[82:83], v[140:141]
.Lbr_na_0_5:
	v_cvt_pk_bf16_f32 v84, v84, v85
	v_cvt_pk_bf16_f32 v85, v86, v87
	v_cvt_pk_bf16_f32 v86, v80, v81
	v_cvt_pk_bf16_f32 v87, v82, v83
	global_store_dwordx4 v[154:155], v[84:87], off offset:256
	s_waitcnt vmcnt(7)
	v_lshlrev_b32_e32 v250, 16, v188
	v_and_b32_e32 v251, 0xffff0000, v188
	v_lshlrev_b32_e32 v252, 16, v189
	v_and_b32_e32 v253, 0xffff0000, v189
	v_lshlrev_b32_e32 v158, 16, v190
	v_and_b32_e32 v159, 0xffff0000, v190
	v_lshlrev_b32_e32 v140, 16, v191
	v_and_b32_e32 v141, 0xffff0000, v191
	v_pk_mul_f32 v[76:77], v[76:77], v[250:251]
	v_pk_mul_f32 v[78:79], v[78:79], v[252:253]
	v_pk_mul_f32 v[72:73], v[72:73], v[158:159]
	v_pk_mul_f32 v[74:75], v[74:75], v[140:141]
	s_cbranch_vccz .Lbr_na_0_6
	v_lshlrev_b32_e32 v250, 16, v242
	v_and_b32_e32 v251, 0xffff0000, v242
	v_lshlrev_b32_e32 v252, 16, v243
	v_and_b32_e32 v253, 0xffff0000, v243
	v_lshlrev_b32_e32 v158, 16, v244
	v_and_b32_e32 v159, 0xffff0000, v244
	v_lshlrev_b32_e32 v140, 16, v245
	v_and_b32_e32 v141, 0xffff0000, v245
	v_pk_add_f32 v[76:77], v[76:77], v[250:251]
	v_pk_add_f32 v[78:79], v[78:79], v[252:253]
	v_pk_add_f32 v[72:73], v[72:73], v[158:159]
	v_pk_add_f32 v[74:75], v[74:75], v[140:141]
.Lbr_na_0_6:
	v_cvt_pk_bf16_f32 v76, v76, v77
	v_cvt_pk_bf16_f32 v77, v78, v79
	v_cvt_pk_bf16_f32 v78, v72, v73
	v_cvt_pk_bf16_f32 v79, v74, v75
	global_store_dwordx4 v[156:157], v[76:79], off
	s_waitcnt vmcnt(7)
	v_lshlrev_b32_e32 v250, 16, v192
	v_and_b32_e32 v251, 0xffff0000, v192
	v_lshlrev_b32_e32 v252, 16, v193
	v_and_b32_e32 v253, 0xffff0000, v193
	v_lshlrev_b32_e32 v158, 16, v194
	v_and_b32_e32 v159, 0xffff0000, v194
	v_lshlrev_b32_e32 v140, 16, v195
	v_and_b32_e32 v141, 0xffff0000, v195
	v_pk_mul_f32 v[68:69], v[68:69], v[250:251]
	v_pk_mul_f32 v[70:71], v[70:71], v[252:253]
	v_pk_mul_f32 v[64:65], v[64:65], v[158:159]
	v_pk_mul_f32 v[66:67], v[66:67], v[140:141]
	s_cbranch_vccz .Lbr_na_0_7
	v_lshlrev_b32_e32 v250, 16, v246
	v_and_b32_e32 v251, 0xffff0000, v246
	v_lshlrev_b32_e32 v252, 16, v247
	v_and_b32_e32 v253, 0xffff0000, v247
	v_lshlrev_b32_e32 v158, 16, v248
	v_and_b32_e32 v159, 0xffff0000, v248
	v_lshlrev_b32_e32 v140, 16, v249
	v_and_b32_e32 v141, 0xffff0000, v249
	v_pk_add_f32 v[68:69], v[68:69], v[250:251]
	v_pk_add_f32 v[70:71], v[70:71], v[252:253]
	v_pk_add_f32 v[64:65], v[64:65], v[158:159]
	v_pk_add_f32 v[66:67], v[66:67], v[140:141]
; __device__ __forceinline__ unsigned cvt_pk_bf16(float lo, float hi) { const f32x2_cv v = {lo, hi}; const bf16x2_cv b = __builtin_convertvector(v, bf16x2_cv); return __builtin_bit_cast(unsigned, b); }
; __device__ __forceinline__ float bf_lo(unsigned w) { return __uint_as_float(w << 16); }
; __device__ __forceinline__ float bf_hi(unsigned w) { return __uint_as_float(w & 0xffff0000u); }
;     __device__ __forceinline__ void operator()(const f32x4 (&acc)[2][2][4][2], const Unit& u, int wr, int wc, int fr, int fq) const {
;     ...
;         for (int ai = 0; ai < 2; ++ai)
; #pragma unroll
;             for (int m = 0; m < 4; ++m) { const int row = row0 + ai * HALF + m * 16;
; #pragma unroll
;                 for (int bj = 0; bj < 2; ++bj) { const int col = col0 + bj * HALF;
;                     const u32x4 g = *(const u32x4*)(G + (size_t)row * GW + gcol0 + col);
;                     float r[8];
;                     r[0] = acc[ai][bj][m][0][0] * bf_lo(g.x); r[1] = acc[ai][bj][m][0][1] * bf_hi(g.x); r[2] = acc[ai][bj][m][0][2] * bf_lo(g.y); r[3] = acc[ai][bj][m][0][3] * bf_hi(g.y);
;                     r[4] = acc[ai][bj][m][1][0] * bf_lo(g.z); r[5] = acc[ai][bj][m][1][1] * bf_hi(g.z); r[6] = acc[ai][bj][m][1][2] * bf_lo(g.w); r[7] = acc[ai][bj][m][1][3] * bf_hi(g.w);
;                     bf16_t* dst = O + (size_t)row * DM + col;
;                     if (add) { const u32x4 o = *(const u32x4*)dst;
;                         r[0] += bf_lo(o.x); r[1] += bf_hi(o.x); r[2] += bf_lo(o.y); r[3] += bf_hi(o.y); r[4] += bf_lo(o.z); r[5] += bf_hi(o.z); r[6] += bf_lo(o.w); r[7] += bf_hi(o.w); }
;                     u32x4 w; w.x = cvt_pk_bf16(r[0], r[1]); w.y = cvt_pk_bf16(r[2], r[3]); w.z = cvt_pk_bf16(r[4], r[5]); w.w = cvt_pk_bf16(r[6], r[7]);
;                     *(u32x4*)dst = w; } }
.Lbr_na_0_7:
	v_cvt_pk_bf16_f32 v68, v68, v69
	v_cvt_pk_bf16_f32 v69, v70, v71
	v_cvt_pk_bf16_f32 v70, v64, v65
	v_cvt_pk_bf16_f32 v71, v66, v67
	global_store_dwordx4 v[156:157], v[68:71], off offset:256
	s_mov_b64 s[28:29], 0x80000
	v_lshl_add_u64 v[144:145], v[144:145], 0, s[28:29]
	v_lshl_add_u64 v[152:153], v[144:145], 0, s[94:95]
	v_lshl_add_u64 v[154:155], v[152:153], 0, s[94:95]
	v_lshl_add_u64 v[156:157], v[154:155], 0, s[94:95]
	global_load_dwordx4 v[164:167], v[142:143], off
	global_load_dwordx4 v[168:171], v[142:143], off offset:256
	v_lshl_add_u64 v[142:143], v[142:143], 0, s[98:99]
	global_load_dwordx4 v[172:175], v[142:143], off
	global_load_dwordx4 v[176:179], v[142:143], off offset:256
	v_lshl_add_u64 v[142:143], v[142:143], 0, s[98:99]
	global_load_dwordx4 v[180:183], v[142:143], off
	global_load_dwordx4 v[184:187], v[142:143], off offset:256
	v_lshl_add_u64 v[142:143], v[142:143], 0, s[98:99]
	global_load_dwordx4 v[188:191], v[142:143], off
	global_load_dwordx4 v[192:195], v[142:143], off offset:256
	s_cbranch_vccz .Lbr_nl_1
	global_load_dwordx4 v[196:199], v[144:145], off
	global_load_dwordx4 v[222:225], v[144:145], off offset:256
	global_load_dwordx4 v[226:229], v[152:153], off
	global_load_dwordx4 v[230:233], v[152:153], off offset:256
	global_load_dwordx4 v[234:237], v[154:155], off
	global_load_dwordx4 v[238:241], v[154:155], off offset:256
	global_load_dwordx4 v[242:245], v[156:157], off
	global_load_dwordx4 v[246:249], v[156:157], off offset:256
.Lbr_nl_1:
	s_waitcnt vmcnt(7)
	v_lshlrev_b32_e32 v250, 16, v164
	v_and_b32_e32 v251, 0xffff0000, v164
	v_lshlrev_b32_e32 v252, 16, v165
	v_and_b32_e32 v253, 0xffff0000, v165
	v_lshlrev_b32_e32 v158, 16, v166
	v_and_b32_e32 v159, 0xffff0000, v166
	v_lshlrev_b32_e32 v140, 16, v167
	v_and_b32_e32 v141, 0xffff0000, v167
	v_pk_mul_f32 v[60:61], v[60:61], v[250:251]
	v_pk_mul_f32 v[62:63], v[62:63], v[252:253]
	v_pk_mul_f32 v[56:57], v[56:57], v[158:159]
	v_pk_mul_f32 v[58:59], v[58:59], v[140:141]
	s_cbranch_vccz .Lbr_na_1_0
	v_lshlrev_b32_e32 v250, 16, v196
	v_and_b32_e32 v251, 0xffff0000, v196
	v_lshlrev_b32_e32 v252, 16, v197
	v_and_b32_e32 v253, 0xffff0000, v197
	v_lshlrev_b32_e32 v158, 16, v198
	v_and_b32_e32 v159, 0xffff0000, v198
	v_lshlrev_b32_e32 v140, 16, v199
	v_and_b32_e32 v141, 0xffff0000, v199
	v_pk_add_f32 v[60:61], v[60:61], v[250:251]
	v_pk_add_f32 v[62:63], v[62:63], v[252:253]
	v_pk_add_f32 v[56:57], v[56:57], v[158:159]
	v_pk_add_f32 v[58:59], v[58:59], v[140:141]
.Lbr_na_1_0:
	v_cvt_pk_bf16_f32 v60, v60, v61
	v_cvt_pk_bf16_f32 v61, v62, v63
	v_cvt_pk_bf16_f32 v62, v56, v57
	v_cvt_pk_bf16_f32 v63, v58, v59
	global_store_dwordx4 v[144:145], v[60:63], off
	s_waitcnt vmcnt(7)
	v_lshlrev_b32_e32 v250, 16, v168
	v_and_b32_e32 v251, 0xffff0000, v168
	v_lshlrev_b32_e32 v252, 16, v169
	v_and_b32_e32 v253, 0xffff0000, v169
	v_lshlrev_b32_e32 v158, 16, v170
	v_and_b32_e32 v159, 0xffff0000, v170
	v_lshlrev_b32_e32 v140, 16, v171
	v_and_b32_e32 v141, 0xffff0000, v171
	v_pk_mul_f32 v[52:53], v[52:53], v[250:251]
	v_pk_mul_f32 v[54:55], v[54:55], v[252:253]
	v_pk_mul_f32 v[48:49], v[48:49], v[158:159]
	v_pk_mul_f32 v[50:51], v[50:51], v[140:141]
	s_cbranch_vccz .Lbr_na_1_1
	v_lshlrev_b32_e32 v250, 16, v222
	v_and_b32_e32 v251, 0xffff0000, v222
	v_lshlrev_b32_e32 v252, 16, v223
	v_and_b32_e32 v253, 0xffff0000, v223
	v_lshlrev_b32_e32 v158, 16, v224
	v_and_b32_e32 v159, 0xffff0000, v224
	v_lshlrev_b32_e32 v140, 16, v225
	v_and_b32_e32 v141, 0xffff0000, v225
	v_pk_add_f32 v[52:53], v[52:53], v[250:251]
	v_pk_add_f32 v[54:55], v[54:55], v[252:253]
	v_pk_add_f32 v[48:49], v[48:49], v[158:159]
	v_pk_add_f32 v[50:51], v[50:51], v[140:141]
.Lbr_na_1_1:
	v_cvt_pk_bf16_f32 v52, v52, v53
	v_cvt_pk_bf16_f32 v53, v54, v55
	v_cvt_pk_bf16_f32 v54, v48, v49
	v_cvt_pk_bf16_f32 v55, v50, v51
	global_store_dwordx4 v[144:145], v[52:55], off offset:256
	s_waitcnt vmcnt(7)
	v_lshlrev_b32_e32 v250, 16, v172
	v_and_b32_e32 v251, 0xffff0000, v172
	v_lshlrev_b32_e32 v252, 16, v173
	v_and_b32_e32 v253, 0xffff0000, v173
	v_lshlrev_b32_e32 v158, 16, v174
	v_and_b32_e32 v159, 0xffff0000, v174
	v_lshlrev_b32_e32 v140, 16, v175
	v_and_b32_e32 v141, 0xffff0000, v175
	v_pk_mul_f32 v[44:45], v[44:45], v[250:251]
	v_pk_mul_f32 v[46:47], v[46:47], v[252:253]
	v_pk_mul_f32 v[40:41], v[40:41], v[158:159]
	v_pk_mul_f32 v[42:43], v[42:43], v[140:141]
	s_cbranch_vccz .Lbr_na_1_2
	v_lshlrev_b32_e32 v250, 16, v226
	v_and_b32_e32 v251, 0xffff0000, v226
	v_lshlrev_b32_e32 v252, 16, v227
	v_and_b32_e32 v253, 0xffff0000, v227
	v_lshlrev_b32_e32 v158, 16, v228
	v_and_b32_e32 v159, 0xffff0000, v228
	v_lshlrev_b32_e32 v140, 16, v229
	v_and_b32_e32 v141, 0xffff0000, v229
	v_pk_add_f32 v[44:45], v[44:45], v[250:251]
	v_pk_add_f32 v[46:47], v[46:47], v[252:253]
	v_pk_add_f32 v[40:41], v[40:41], v[158:159]
	v_pk_add_f32 v[42:43], v[42:43], v[140:141]
.Lbr_na_1_2:
	v_cvt_pk_bf16_f32 v44, v44, v45
	v_cvt_pk_bf16_f32 v45, v46, v47
	v_cvt_pk_bf16_f32 v46, v40, v41
	v_cvt_pk_bf16_f32 v47, v42, v43
	global_store_dwordx4 v[152:153], v[44:47], off
	s_waitcnt vmcnt(7)
	v_lshlrev_b32_e32 v250, 16, v176
	v_and_b32_e32 v251, 0xffff0000, v176
	v_lshlrev_b32_e32 v252, 16, v177
	v_and_b32_e32 v253, 0xffff0000, v177
	v_lshlrev_b32_e32 v158, 16, v178
	v_and_b32_e32 v159, 0xffff0000, v178
	v_lshlrev_b32_e32 v140, 16, v179
	v_and_b32_e32 v141, 0xffff0000, v179
	v_pk_mul_f32 v[36:37], v[36:37], v[250:251]
	v_pk_mul_f32 v[38:39], v[38:39], v[252:253]
	v_pk_mul_f32 v[32:33], v[32:33], v[158:159]
	v_pk_mul_f32 v[34:35], v[34:35], v[140:141]
	s_cbranch_vccz .Lbr_na_1_3
	v_lshlrev_b32_e32 v250, 16, v230
	v_and_b32_e32 v251, 0xffff0000, v230
	v_lshlrev_b32_e32 v252, 16, v231
	v_and_b32_e32 v253, 0xffff0000, v231
	v_lshlrev_b32_e32 v158, 16, v232
	v_and_b32_e32 v159, 0xffff0000, v232
	v_lshlrev_b32_e32 v140, 16, v233
	v_and_b32_e32 v141, 0xffff0000, v233
	v_pk_add_f32 v[36:37], v[36:37], v[250:251]
	v_pk_add_f32 v[38:39], v[38:39], v[252:253]
	v_pk_add_f32 v[32:33], v[32:33], v[158:159]
	v_pk_add_f32 v[34:35], v[34:35], v[140:141]
; __device__ __forceinline__ unsigned cvt_pk_bf16(float lo, float hi) { const f32x2_cv v = {lo, hi}; const bf16x2_cv b = __builtin_convertvector(v, bf16x2_cv); return __builtin_bit_cast(unsigned, b); }
; __device__ __forceinline__ float bf_lo(unsigned w) { return __uint_as_float(w << 16); }
; __device__ __forceinline__ float bf_hi(unsigned w) { return __uint_as_float(w & 0xffff0000u); }
; #define PG8_BAR __builtin_amdgcn_s_barrier()
;     __device__ __forceinline__ void operator()(const f32x4 (&acc)[2][2][4][2], const Unit& u, int wr, int wc, int fr, int fq) const {
;     ...
;             for (int m = 0; m < 4; ++m) { const int row = row0 + ai * HALF + m * 16;
; #pragma unroll
;                 for (int bj = 0; bj < 2; ++bj) { const int col = col0 + bj * HALF;
;                     const u32x4 g = *(const u32x4*)(G + (size_t)row * GW + gcol0 + col);
;                     float r[8];
;                     r[0] = acc[ai][bj][m][0][0] * bf_lo(g.x); r[1] = acc[ai][bj][m][0][1] * bf_hi(g.x); r[2] = acc[ai][bj][m][0][2] * bf_lo(g.y); r[3] = acc[ai][bj][m][0][3] * bf_hi(g.y);
;                     r[4] = acc[ai][bj][m][1][0] * bf_lo(g.z); r[5] = acc[ai][bj][m][1][1] * bf_hi(g.z); r[6] = acc[ai][bj][m][1][2] * bf_lo(g.w); r[7] = acc[ai][bj][m][1][3] * bf_hi(g.w);
;                     bf16_t* dst = O + (size_t)row * DM + col;
;                     if (add) { const u32x4 o = *(const u32x4*)dst;
;                         r[0] += bf_lo(o.x); r[1] += bf_hi(o.x); r[2] += bf_lo(o.y); r[3] += bf_hi(o.y); r[4] += bf_lo(o.z); r[5] += bf_hi(o.z); r[6] += bf_lo(o.w); r[7] += bf_hi(o.w); }
;                     u32x4 w; w.x = cvt_pk_bf16(r[0], r[1]); w.y = cvt_pk_bf16(r[2], r[3]); w.z = cvt_pk_bf16(r[4], r[5]); w.w = cvt_pk_bf16(r[6], r[7]);
;                     *(u32x4*)dst = w; } }
; template <class Epi, class Sched, bool ALIGN_EPI = false, bool SP2 = false>
; __device__ __forceinline__ void gemm_phase(PG8_LAS unsigned char* lds, const Gemm g, const Sched& S, const Epi& E) {
;     ...
;         cur = nxt; cA = nA; cB = nB; ++ui;
;         if constexpr (ALIGN_EPI) { if (wr == 1) PG8_BAR; }
.Lbr_na_1_3:
	v_cvt_pk_bf16_f32 v36, v36, v37
	v_cvt_pk_bf16_f32 v37, v38, v39
	v_cvt_pk_bf16_f32 v38, v32, v33
	v_cvt_pk_bf16_f32 v39, v34, v35
	global_store_dwordx4 v[152:153], v[36:39], off offset:256
	s_waitcnt vmcnt(7)
	v_lshlrev_b32_e32 v250, 16, v180
	v_and_b32_e32 v251, 0xffff0000, v180
	v_lshlrev_b32_e32 v252, 16, v181
	v_and_b32_e32 v253, 0xffff0000, v181
	v_lshlrev_b32_e32 v158, 16, v182
	v_and_b32_e32 v159, 0xffff0000, v182
	v_lshlrev_b32_e32 v140, 16, v183
	v_and_b32_e32 v141, 0xffff0000, v183
	v_pk_mul_f32 v[28:29], v[28:29], v[250:251]
	v_pk_mul_f32 v[30:31], v[30:31], v[252:253]
	v_pk_mul_f32 v[24:25], v[24:25], v[158:159]
	v_pk_mul_f32 v[26:27], v[26:27], v[140:141]
	s_cbranch_vccz .Lbr_na_1_4
	v_lshlrev_b32_e32 v250, 16, v234
	v_and_b32_e32 v251, 0xffff0000, v234
	v_lshlrev_b32_e32 v252, 16, v235
	v_and_b32_e32 v253, 0xffff0000, v235
	v_lshlrev_b32_e32 v158, 16, v236
	v_and_b32_e32 v159, 0xffff0000, v236
	v_lshlrev_b32_e32 v140, 16, v237
	v_and_b32_e32 v141, 0xffff0000, v237
	v_pk_add_f32 v[28:29], v[28:29], v[250:251]
	v_pk_add_f32 v[30:31], v[30:31], v[252:253]
	v_pk_add_f32 v[24:25], v[24:25], v[158:159]
	v_pk_add_f32 v[26:27], v[26:27], v[140:141]
.Lbr_na_1_4:
	v_cvt_pk_bf16_f32 v28, v28, v29
	v_cvt_pk_bf16_f32 v29, v30, v31
	v_cvt_pk_bf16_f32 v30, v24, v25
	v_cvt_pk_bf16_f32 v31, v26, v27
	global_store_dwordx4 v[154:155], v[28:31], off
	s_waitcnt vmcnt(7)
	v_lshlrev_b32_e32 v250, 16, v184
	v_and_b32_e32 v251, 0xffff0000, v184
	v_lshlrev_b32_e32 v252, 16, v185
	v_and_b32_e32 v253, 0xffff0000, v185
	v_lshlrev_b32_e32 v158, 16, v186
	v_and_b32_e32 v159, 0xffff0000, v186
	v_lshlrev_b32_e32 v140, 16, v187
	v_and_b32_e32 v141, 0xffff0000, v187
	v_pk_mul_f32 v[20:21], v[20:21], v[250:251]
	v_pk_mul_f32 v[22:23], v[22:23], v[252:253]
	v_pk_mul_f32 v[16:17], v[16:17], v[158:159]
	v_pk_mul_f32 v[18:19], v[18:19], v[140:141]
	s_cbranch_vccz .Lbr_na_1_5
	v_lshlrev_b32_e32 v250, 16, v238
	v_and_b32_e32 v251, 0xffff0000, v238
	v_lshlrev_b32_e32 v252, 16, v239
	v_and_b32_e32 v253, 0xffff0000, v239
	v_lshlrev_b32_e32 v158, 16, v240
	v_and_b32_e32 v159, 0xffff0000, v240
	v_lshlrev_b32_e32 v140, 16, v241
	v_and_b32_e32 v141, 0xffff0000, v241
	v_pk_add_f32 v[20:21], v[20:21], v[250:251]
	v_pk_add_f32 v[22:23], v[22:23], v[252:253]
	v_pk_add_f32 v[16:17], v[16:17], v[158:159]
	v_pk_add_f32 v[18:19], v[18:19], v[140:141]
.Lbr_na_1_5:
	v_cvt_pk_bf16_f32 v20, v20, v21
	v_cvt_pk_bf16_f32 v21, v22, v23
	v_cvt_pk_bf16_f32 v22, v16, v17
	v_cvt_pk_bf16_f32 v23, v18, v19
	global_store_dwordx4 v[154:155], v[20:23], off offset:256
	s_waitcnt vmcnt(7)
	v_lshlrev_b32_e32 v250, 16, v188
	v_and_b32_e32 v251, 0xffff0000, v188
	v_lshlrev_b32_e32 v252, 16, v189
	v_and_b32_e32 v253, 0xffff0000, v189
	v_lshlrev_b32_e32 v158, 16, v190
	v_and_b32_e32 v159, 0xffff0000, v190
	v_lshlrev_b32_e32 v140, 16, v191
	v_and_b32_e32 v141, 0xffff0000, v191
	v_pk_mul_f32 v[12:13], v[12:13], v[250:251]
	v_pk_mul_f32 v[14:15], v[14:15], v[252:253]
	v_pk_mul_f32 v[8:9], v[8:9], v[158:159]
	v_pk_mul_f32 v[10:11], v[10:11], v[140:141]
	s_cbranch_vccz .Lbr_na_1_6
	v_lshlrev_b32_e32 v250, 16, v242
	v_and_b32_e32 v251, 0xffff0000, v242
	v_lshlrev_b32_e32 v252, 16, v243
	v_and_b32_e32 v253, 0xffff0000, v243
	v_lshlrev_b32_e32 v158, 16, v244
	v_and_b32_e32 v159, 0xffff0000, v244
	v_lshlrev_b32_e32 v140, 16, v245
	v_and_b32_e32 v141, 0xffff0000, v245
	v_pk_add_f32 v[12:13], v[12:13], v[250:251]
	v_pk_add_f32 v[14:15], v[14:15], v[252:253]
	v_pk_add_f32 v[8:9], v[8:9], v[158:159]
	v_pk_add_f32 v[10:11], v[10:11], v[140:141]
.Lbr_na_1_6:
	v_cvt_pk_bf16_f32 v12, v12, v13
	v_cvt_pk_bf16_f32 v13, v14, v15
	v_cvt_pk_bf16_f32 v14, v8, v9
	v_cvt_pk_bf16_f32 v15, v10, v11
	global_store_dwordx4 v[156:157], v[12:15], off
	s_waitcnt vmcnt(7)
	v_lshlrev_b32_e32 v250, 16, v192
	v_and_b32_e32 v251, 0xffff0000, v192
	v_lshlrev_b32_e32 v252, 16, v193
	v_and_b32_e32 v253, 0xffff0000, v193
	v_lshlrev_b32_e32 v158, 16, v194
	v_and_b32_e32 v159, 0xffff0000, v194
	v_lshlrev_b32_e32 v140, 16, v195
	v_and_b32_e32 v141, 0xffff0000, v195
	v_pk_mul_f32 v[4:5], v[4:5], v[250:251]
	v_pk_mul_f32 v[6:7], v[6:7], v[252:253]
	v_pk_mul_f32 v[0:1], v[0:1], v[158:159]
	v_pk_mul_f32 v[2:3], v[2:3], v[140:141]
	s_cbranch_vccz .Lbr_na_1_7
	v_lshlrev_b32_e32 v250, 16, v246
	v_and_b32_e32 v251, 0xffff0000, v246
	v_lshlrev_b32_e32 v252, 16, v247
	v_and_b32_e32 v253, 0xffff0000, v247
	v_lshlrev_b32_e32 v158, 16, v248
	v_and_b32_e32 v159, 0xffff0000, v248
	v_lshlrev_b32_e32 v140, 16, v249
	v_and_b32_e32 v141, 0xffff0000, v249
	v_pk_add_f32 v[4:5], v[4:5], v[250:251]
	v_pk_add_f32 v[6:7], v[6:7], v[252:253]
	v_pk_add_f32 v[0:1], v[0:1], v[158:159]
	v_pk_add_f32 v[2:3], v[2:3], v[140:141]
.Lbr_na_1_7:
	v_cvt_pk_bf16_f32 v4, v4, v5
	v_cvt_pk_bf16_f32 v5, v6, v7
	v_cvt_pk_bf16_f32 v6, v0, v1
	v_cvt_pk_bf16_f32 v7, v2, v3
	global_store_dwordx4 v[156:157], v[4:7], off offset:256
	s_andn2_b64 vcc, exec, s[44:45]
	s_mov_b64 s[4:5], -1
	s_cbranch_vccnz .LBB0_82
	s_andn2_b64 vcc, exec, s[10:11]
	s_cbranch_vccnz .LBB0_81
	s_barrier
	s_branch .LBB0_81
